# NSA attention: first K/V tile of the selection and window branches requested one branch earlier (loads hoisted above the previous branch)
# speedup vs baseline: 1.0058x; 1.0013x over previous
.LBB0_4365:
	s_load_dwordx4 s[88:91], s[0:1], 0x1b8
	s_load_dwordx4 s[92:95], s[0:1], 0x1c8
	s_abs_i32 s3, s68
	s_mul_hi_u32 s4, s3, s61
	s_mul_i32 s5, s4, s60
	s_ashr_i32 s2, s68, 31
	s_sub_i32 s3, s3, s5
	s_xor_b32 s2, s2, s56
	s_add_i32 s5, s4, 1
	s_sub_i32 s6, s3, s60
	s_cmp_ge_u32 s3, s60
	s_cselect_b32 s4, s5, s4
	s_cselect_b32 s3, s6, s3
	s_add_i32 s5, s4, 1
	s_cmp_ge_u32 s3, s60
	s_cselect_b32 s3, s5, s4
	s_xor_b32 s3, s3, s2
	s_sub_i32 s3, s3, s2
	s_mul_i32 s73, s3, s42
	s_sub_i32 s54, s68, s73
	s_ashr_i32 s55, s54, 31
	s_lshr_b32 s2, s55, 27
	s_add_i32 s2, s54, s2
	s_ashr_i32 s4, s2, 5
	s_and_b32 s52, s2, 0xffffffe0
	s_not_b32 s6, s4
	s_sub_i32 s2, s54, s52
	s_and_b32 s5, s3, 1
	s_add_i32 s6, s57, s6
	s_cmp_eq_u32 s5, 0
	s_cselect_b32 s4, s4, s6
	s_mul_i32 s3, s3, s57
	s_add_i32 s4, s4, s3
	s_lshl_b32 s72, s4, 6
	s_ashr_i32 s50, s2, 2
	s_and_b32 s74, s54, 3
	s_sub_i32 s75, 0xfc0, s72
	s_lshl_b32 s3, s74, 2
	s_or_b32 s48, s75, s59
	s_ashr_i32 s51, s50, 31
	s_add_i32 s3, s3, s58
	s_lshl_b64 s[4:5], s[50:51], 12
	s_ashr_i32 s49, s48, 31
	s_add_u32 s69, s4, s48
	s_addc_u32 s71, s5, s49
	v_mov_b32_e32 v3, s71
	v_or_b32_e32 v2, s69, v168
	s_lshl_b32 s38, s3, 6
	s_mul_i32 s4, s3, 3
	s_ashr_i32 s3, s2, 31
	v_lshlrev_b64 v[4:5], 11, v[2:3]
	s_ashr_i32 s39, s38, 31
	s_ashr_i32 s5, s4, 31
	v_mad_u64_u32 v[2:3], s[6:7], v2, s62, v[172:173]
	s_lshl_b64 s[2:3], s[2:3], 15
	v_mad_i32_i24 v3, s71, v182, v3
	s_add_u32 s6, s26, s2
	v_lshl_add_u64 v[4:5], s[24:25], 0, v[4:5]
	v_lshl_add_u64 v[2:3], s[4:5], 1, v[2:3]
	s_addc_u32 s7, s27, s3
	s_lshl_b64 s[4:5], s[48:49], 3
	v_lshl_add_u64 v[4:5], s[38:39], 1, v[4:5]
	s_add_u32 s4, s6, s4
	v_lshl_add_u64 v[4:5], v[4:5], 0, v[170:171]
	s_addc_u32 s5, s7, s5
	v_mov_b32_e32 v0, v169
	global_load_dwordx4 v[144:147], v[4:5], off
	global_load_dwordx4 v[148:151], v[4:5], off offset:32
	global_load_dwordx4 v[152:155], v[4:5], off offset:64
	global_load_dwordx4 v[156:159], v[4:5], off offset:96
	global_load_dword v188, v[2:3], off
	global_load_ushort v187, v[2:3], off offset:4
	global_load_dwordx2 v[120:121], v183, s[4:5]
	s_add_u32 s4, s16, s2
	v_add_u32_e32 v3, s70, v0
	v_ashrrev_i32_e32 v2, 31, v3
	v_lshrrev_b32_e32 v2, 29, v2
	v_add_u32_e32 v4, v3, v2
	v_ashrrev_i32_e32 v2, 3, v4
	v_and_b32_e32 v4, 0x1ffffff8, v4
	v_sub_u32_e32 v3, v3, v4
	s_addc_u32 s5, s17, s3
	v_lshlrev_b32_e32 v88, 3, v3
	v_ashrrev_i32_e32 v3, 31, v2
	s_add_u32 s2, s18, s2
	v_lshlrev_b64 v[90:91], 7, v[2:3]
	v_ashrrev_i32_e32 v89, 31, v88
	s_addc_u32 s3, s19, s3
	v_lshl_add_u64 v[4:5], s[4:5], 0, v[90:91]
	v_lshlrev_b64 v[6:7], 1, v[88:89]
	v_lshl_add_u64 v[4:5], v[4:5], 0, v[6:7]
	v_lshl_add_u64 v[8:9], s[2:3], 0, v[90:91]
	v_lshl_add_u64 v[6:7], v[8:9], 0, v[6:7]
	global_load_dwordx4 v[80:83], v[4:5], off
	global_load_dwordx4 v[84:87], v[6:7], off
	v_add_u32_e32 v234, s70, v169
	v_lshrrev_b32_e32 v235, 3, v234
	v_and_b32_e32 v234, 7, v234
	v_lshlrev_b32_e32 v234, 4, v234
	v_lshl_or_b32 v234, v235, 9, v234
	s_lshl_b64 s[96:97], s[50:51], 21
	s_lshl_b32 s99, s74, 7
	s_add_u32 s96, s96, s99
	s_addc_u32 s97, s97, 0
	s_waitcnt lgkmcnt(0)
	s_add_u32 s86, s88, s96
	s_addc_u32 s87, s89, s97
	s_add_u32 s82, s90, s96
	s_addc_u32 s83, s91, s97
	global_load_dwordx4 v[244:247], v234, s[86:87]
	global_load_dwordx4 v[248:251], v234, s[82:83]
	s_sub_i32 s2, 0xfe0, s72
	s_ashr_i32 s2, s2, 4
	s_min_i32 s2, s2, 0xfe
	s_ashr_i32 s3, s2, 31
	s_lshr_b32 s3, s3, 26
	s_add_i32 s2, s2, s3
	s_ashr_i32 s76, s2, 6
	s_ashr_i32 s2, s75, 31
	s_lshr_b32 s2, s2, 22
	s_add_i32 s2, s48, s2
	s_ashr_i32 s2, s2, 10
	s_min_i32 s20, s2, s76
	s_cmp_lt_i32 s20, 0
	s_waitcnt vmcnt(16)
	v_mul_lo_u32 v96, v2, s63
	v_mul_lo_u32 v97, v2, s64
	v_lshlrev_b32_e32 v98, 1, v88
	s_barrier
	s_cbranch_scc1 .LBB0_4372
	v_bfe_u32 v2, v0, 5, 1
	v_and_b32_e32 v3, 31, v0
	s_lshl_b64 s[2:3], s[54:55], 15
	s_waitcnt vmcnt(15)
	v_or_b32_e32 v100, s48, v3
	v_lshlrev_b32_e32 v4, 2, v2
	v_mul_u32_u24_e32 v34, 0x48, v3
	v_lshlrev_b32_e32 v102, 4, v2
	v_lshl_add_u32 v103, v2, 6, v184
	v_lshl_add_u64 v[2:3], s[2:3], 0, v[90:91]
	s_ashr_i32 s53, s52, 31
	v_lshrrev_b32_e32 v5, 2, v0
	v_and_b32_e32 v32, 16, v0
	v_lshlrev_b32_e32 v0, 2, v0
	v_lshl_add_u64 v[2:3], v[88:89], 1, v[2:3]
	s_lshl_b64 s[2:3], s[52:53], 15
	v_and_b32_e32 v33, 12, v0
	v_mov_b32_e32 v0, s3
	v_subrev_co_u32_e32 v2, vcc, s2, v2
	v_and_or_b32 v5, v5, 3, v4
	s_nop 0
	v_subb_co_u32_e32 v3, vcc, v3, v0, vcc
	v_mov_b32_e32 v30, v1
	v_mov_b32_e32 v31, v1
	v_mul_u32_u24_e32 v101, 0xc0, v5
	s_waitcnt vmcnt(14)
	v_or_b32_e32 v104, 59, v4
	v_lshl_add_u64 v[92:93], s[30:31], 0, v[2:3]
	v_lshl_add_u64 v[94:95], s[34:35], 0, v[2:3]
	v_mov_b32_e32 v0, v1
	v_mov_b32_e32 v2, v1
	v_mov_b32_e32 v3, v1
	v_mov_b32_e32 v4, v1
	v_mov_b32_e32 v5, v1
	v_mov_b32_e32 v6, v1
	v_mov_b32_e32 v7, v1
	v_mov_b32_e32 v8, v1
	v_mov_b32_e32 v9, v1
	v_mov_b32_e32 v10, v1
	v_mov_b32_e32 v11, v1
	v_mov_b32_e32 v12, v1
	v_mov_b32_e32 v13, v1
	v_mov_b32_e32 v14, v1
	v_mov_b32_e32 v15, v1
	v_mov_b32_e32 v16, v1
	v_mov_b32_e32 v17, v1
	v_mov_b32_e32 v18, v1
	v_mov_b32_e32 v19, v1
	v_mov_b32_e32 v20, v1
	v_mov_b32_e32 v21, v1
	v_mov_b32_e32 v22, v1
	v_mov_b32_e32 v23, v1
	v_mov_b32_e32 v24, v1
	v_mov_b32_e32 v25, v1
	v_mov_b32_e32 v26, v1
	v_mov_b32_e32 v27, v1
	v_mov_b32_e32 v28, v1
	v_mov_b32_e32 v29, v1
	v_lshlrev_b32_e32 v105, 1, v34
	v_lshlrev_b32_e32 v106, 1, v32
	v_lshlrev_b32_e32 v107, 1, v33
	v_mov_b64_e32 v[62:63], v[30:31]
	s_add_i32 s77, s20, 1
	s_mov_b32 s53, 0
	v_mov_b32_e32 v99, 0
	s_waitcnt vmcnt(13)
	v_mov_b32_e32 v108, 0xf149f2ca
	v_mov_b64_e32 v[60:61], v[28:29]
	v_mov_b64_e32 v[58:59], v[26:27]
	v_mov_b64_e32 v[56:57], v[24:25]
	v_mov_b64_e32 v[54:55], v[22:23]
	v_mov_b64_e32 v[52:53], v[20:21]
	v_mov_b64_e32 v[50:51], v[18:19]
	v_mov_b64_e32 v[48:49], v[16:17]
	v_mov_b64_e32 v[46:47], v[14:15]
	v_mov_b64_e32 v[44:45], v[12:13]
	v_mov_b64_e32 v[42:43], v[10:11]
	v_mov_b64_e32 v[40:41], v[8:9]
	v_mov_b64_e32 v[38:39], v[6:7]
	v_mov_b64_e32 v[36:37], v[4:5]
	v_mov_b64_e32 v[34:35], v[2:3]
	v_mov_b64_e32 v[32:33], v[0:1]
	s_branch .LBB0_4368

.LBB0_4380:
	s_or_b64 exec, exec, s[2:3]
	s_load_dwordx4 s[4:7], s[0:1], 0x1b8
	v_mov_b32_e32 v0, v169
	s_lshl_b64 s[10:11], s[50:51], 21
	s_waitcnt lgkmcnt(0)
	s_add_u32 s2, s4, s10
	v_add_u32_e32 v3, s70, v0
	v_ashrrev_i32_e32 v2, 31, v3
	s_addc_u32 s3, s5, s11
	s_lshl_b32 s8, s74, 7
	v_lshrrev_b32_e32 v2, 29, v2
	s_add_u32 s2, s2, s8
	v_add_u32_e32 v4, v3, v2
	s_addc_u32 s3, s3, 0
	v_ashrrev_i32_e32 v2, 3, v4
	v_and_b32_e32 v4, 0x1ffffff8, v4
	s_add_u32 s9, s6, s10
	v_sub_u32_e32 v3, v3, v4
	s_addc_u32 s12, s7, s11
	s_waitcnt vmcnt(10)
	v_lshlrev_b32_e32 v122, 3, v3
	v_ashrrev_i32_e32 v3, 31, v2
	s_add_u32 s8, s9, s8
	s_waitcnt vmcnt(9)
	v_lshlrev_b64 v[124:125], 9, v[2:3]
	v_ashrrev_i32_e32 v123, 31, v122
	s_addc_u32 s9, s12, 0
	v_lshl_add_u64 v[4:5], s[2:3], 0, v[124:125]
	v_lshlrev_b64 v[6:7], 1, v[122:123]
	v_lshl_add_u64 v[4:5], v[4:5], 0, v[6:7]
	v_lshl_add_u64 v[8:9], s[8:9], 0, v[124:125]
	v_lshl_add_u64 v[6:7], v[8:9], 0, v[6:7]
	s_waitcnt vmcnt(0)
	v_mov_b32_e32 v112, v244
	v_mov_b32_e32 v113, v245
	v_mov_b32_e32 v114, v246
	v_mov_b32_e32 v115, v247
	v_mov_b32_e32 v116, v248
	v_mov_b32_e32 v117, v249
	v_mov_b32_e32 v118, v250
	v_mov_b32_e32 v119, v251
	s_sub_i32 s99, 0xdc0, s72
	s_max_i32 s99, s99, -1
	s_add_i32 s99, s99, 1
	s_and_b32 s99, s99, 0xffffffc0
	s_lshl_b32 s99, s99, 9
	s_add_u32 s100, s96, s99
	s_addc_u32 s101, s97, 0
	s_add_u32 s86, s92, s100
	s_addc_u32 s87, s93, s101
	s_add_u32 s82, s94, s100
	s_addc_u32 s83, s95, s101
	global_load_dwordx4 v[236:239], v234, s[86:87]
	global_load_dwordx4 v[240:243], v234, s[82:83]
	s_sub_i32 s2, 0x103f, s72
	s_ashr_i32 s3, s2, 31
	s_lshr_b32 s3, s3, 26
	s_add_i32 s2, s2, s3
	s_ashr_i32 s8, s2, 6
	s_ashr_i32 s2, s75, 6
	s_add_i32 s3, s2, 1
	s_min_i32 s14, s3, s8
	s_cmp_lt_i32 s14, 1
	v_mul_lo_u32 v130, v2, s63
	v_mul_lo_u32 v131, v2, s64
	s_barrier
	s_cbranch_scc1 .LBB0_4390
	v_bfe_u32 v2, v0, 5, 1
	v_and_b32_e32 v3, 31, v0
	s_sub_i32 s3, s67, s73
	v_or_b32_e32 v132, s48, v3
	v_lshlrev_b32_e32 v133, 2, v2
	v_mul_u32_u24_e32 v66, 0x48, v3
	v_lshlrev_b32_e32 v135, 4, v2
	v_lshl_add_u64 v[2:3], s[10:11], 0, v[124:125]
	s_and_b32 s3, s3, 3
	v_lshrrev_b32_e32 v4, 2, v0
	v_lshl_or_b32 v2, s3, 7, v2
	s_ashr_i32 s3, s2, 31
	v_and_or_b32 v4, v4, 3, v133
	v_lshl_add_u64 v[2:3], v[122:123], 1, v[2:3]
	s_add_u32 s2, s2, 1
	v_mul_u32_u24_e32 v134, 0xc0, v4
	v_lshl_add_u64 v[4:5], s[4:5], 0, v[2:3]
	v_lshl_add_u64 v[2:3], s[6:7], 0, v[2:3]
	s_addc_u32 s3, s3, 0
	s_ashr_i32 s9, s8, 31
	v_and_b32_e32 v64, 16, v0
	v_lshlrev_b32_e32 v0, 2, v0
	v_lshl_add_u64 v[128:129], v[2:3], 0, s[36:37]
	v_mov_b64_e32 v[2:3], s[8:9]
	v_and_b32_e32 v65, 12, v0
	v_cmp_lt_i64_e32 vcc, s[2:3], v[2:3]
	v_mov_b32_e32 v30, v1
	v_mov_b32_e32 v31, v1
	v_lshl_add_u64 v[126:127], v[4:5], 0, s[36:37]
	s_and_b64 s[12:13], vcc, exec
	v_mov_b32_e32 v0, v1
	v_mov_b32_e32 v2, v1
	v_mov_b32_e32 v3, v1
	v_mov_b32_e32 v4, v1
	v_mov_b32_e32 v5, v1
	v_mov_b32_e32 v6, v1
	v_mov_b32_e32 v7, v1
	v_mov_b32_e32 v8, v1
	v_mov_b32_e32 v9, v1
	v_mov_b32_e32 v10, v1
	v_mov_b32_e32 v11, v1
	v_mov_b32_e32 v12, v1
	v_mov_b32_e32 v13, v1
	v_mov_b32_e32 v14, v1
	v_mov_b32_e32 v15, v1
	v_mov_b32_e32 v16, v1
	v_mov_b32_e32 v17, v1
	v_mov_b32_e32 v18, v1
	v_mov_b32_e32 v19, v1
	v_mov_b32_e32 v20, v1
	v_mov_b32_e32 v21, v1
	v_mov_b32_e32 v22, v1
	v_mov_b32_e32 v23, v1
	v_mov_b32_e32 v24, v1
	v_mov_b32_e32 v25, v1
	v_mov_b32_e32 v26, v1
	v_mov_b32_e32 v27, v1
	v_mov_b32_e32 v28, v1
	v_mov_b32_e32 v29, v1
	v_lshlrev_b32_e32 v136, 1, v66
	v_lshlrev_b32_e32 v137, 1, v64
	v_lshlrev_b32_e32 v138, 1, v65
	s_waitcnt vmcnt(2)
	v_mov_b64_e32 v[94:95], v[30:31]
	s_cselect_b32 s9, s2, s8
	v_mov_b32_e32 v189, 0
	v_mov_b32_e32 v139, 0xf149f2ca
	s_mov_b32 s98, 1
	v_mov_b32_e32 v212, 0
	v_mov_b32_e32 v213, 0
	v_mov_b32_e32 v214, 0
	v_mov_b32_e32 v215, 0
	v_mov_b32_e32 v216, 0
	v_mov_b32_e32 v217, 0
	v_mov_b32_e32 v218, 0
	v_mov_b32_e32 v219, 0
	v_mov_b32_e32 v220, 0
	v_mov_b32_e32 v221, 0
	v_mov_b32_e32 v222, 0
	v_mov_b32_e32 v223, 0
	v_mov_b32_e32 v224, 0
	v_mov_b32_e32 v225, 0
	v_mov_b32_e32 v226, 0
	v_mov_b32_e32 v227, 0
	v_mov_b32_e32 v228, 0
	v_mov_b32_e32 v229, v139
	s_mov_b64 s[2:3], 0
	s_mov_b32 s15, 63
	v_mov_b64_e32 v[92:93], v[28:29]
	v_mov_b64_e32 v[90:91], v[26:27]
	v_mov_b64_e32 v[88:89], v[24:25]
	v_mov_b64_e32 v[86:87], v[22:23]
	v_mov_b64_e32 v[84:85], v[20:21]
	v_mov_b64_e32 v[82:83], v[18:19]
	v_mov_b64_e32 v[80:81], v[16:17]
	v_mov_b64_e32 v[78:79], v[14:15]
	v_mov_b64_e32 v[76:77], v[12:13]
	v_mov_b64_e32 v[74:75], v[10:11]
	v_mov_b64_e32 v[72:73], v[8:9]
	v_mov_b64_e32 v[70:71], v[6:7]
	v_mov_b64_e32 v[68:69], v[4:5]
	v_mov_b64_e32 v[66:67], v[2:3]
	v_mov_b64_e32 v[64:65], v[0:1]

.LBB0_4396:
	s_load_dwordx4 s[4:7], s[0:1], 0x1c8
	s_lshl_b64 s[2:3], s[2:3], 1
	v_mov_b32_e32 v0, v169
	s_waitcnt lgkmcnt(0)
	s_add_u32 s4, s4, s2
	s_addc_u32 s5, s5, s3
	s_lshl_b32 s9, s9, 1
	s_add_u32 s4, s4, s9
	v_add_u32_e32 v3, s70, v0
	s_addc_u32 s5, s5, 0
	v_ashrrev_i32_e32 v2, 31, v3
	s_add_u32 s2, s6, s2
	v_lshrrev_b32_e32 v2, 29, v2
	s_addc_u32 s3, s7, s3
	v_add_u32_e32 v4, v3, v2
	s_add_u32 s2, s2, s9
	v_ashrrev_i32_e32 v2, 3, v4
	v_and_b32_e32 v4, 0x1ffffff8, v4
	s_addc_u32 s3, s3, 0
	s_sub_i32 s6, 0xdc0, s72
	v_sub_u32_e32 v3, v3, v4
	s_max_i32 s6, s6, -1
	v_lshlrev_b32_e32 v176, 3, v3
	v_ashrrev_i32_e32 v3, 31, v2
	s_add_i32 s6, s6, 1
	v_lshlrev_b64 v[4:5], 9, v[2:3]
	v_ashrrev_i32_e32 v177, 31, v176
	v_lshl_add_u64 v[6:7], s[4:5], 0, v[4:5]
	v_lshlrev_b64 v[8:9], 1, v[176:177]
	s_and_b32 s20, s6, 0xffffffc0
	v_lshl_add_u64 v[178:179], v[6:7], 0, v[8:9]
	v_lshl_add_u64 v[4:5], s[2:3], 0, v[4:5]
	s_lshl_b64 s[2:3], s[20:21], 9
	v_lshl_add_u64 v[180:181], v[4:5], 0, v[8:9]
	v_lshl_add_u64 v[4:5], v[178:179], 0, s[2:3]
	v_lshl_add_u64 v[4:5], v[180:181], 0, s[2:3]
	s_waitcnt vmcnt(0)
	v_mov_b32_e32 v160, v236
	v_mov_b32_e32 v161, v237
	v_mov_b32_e32 v162, v238
	v_mov_b32_e32 v163, v239
	v_mov_b32_e32 v164, v240
	v_mov_b32_e32 v165, v241
	v_mov_b32_e32 v166, v242
	v_mov_b32_e32 v167, v243
	s_add_i32 s2, s48, 0xfffffe01
	ds_bpermute_b32 v177, v175, v189
	s_lshr_b32 s4, s6, 6
	s_lshr_b32 s2, s2, 6
	s_addk_i32 s72, 0xf23f
	s_max_u32 s2, s2, s4
	s_cmp_lt_i32 s72, 0
	s_cselect_b32 s6, s2, s4
	s_cmp_ge_u32 s4, s6
	v_mul_lo_u32 v190, v2, s63
	v_mul_lo_u32 v191, v2, s64
	s_waitcnt lgkmcnt(0)
	s_barrier
	s_cbranch_scc1 .LBB0_4401
	s_lshl_b32 s2, s4, 6
	s_add_i32 s20, s2, 64
	s_mov_b32 s2, 0
	s_branch .LBB0_4399
